# mix part 2, last layer: fourth-round fnet items placed on the virtual blocks whose gMLP item is skipped (no virtual block runs four items)
# speedup vs baseline: 1.0273x; 1.0084x over previous
; DI void phase_mix(KP p, int l, char* lds) {
;     ...
;   for (int it = lb; it < e7; it += nlb) {
;     if (it >= e6) {
;       const int i2 = it - e6; const int mpb = upd ? 18 : 16; const int mloc = i2 >> 1, nt = i2 & 1;
;       const int mt = (2 * xcd + mloc / mpb) * 18 + (mloc % mpb);
;     ...
;       const int i2 = it - e5; const int bl = i2 / 36, rem = i2 % 36; const int cpl = rem >> 2, g = rem & 3;
;       const int ch = (2 * xcd + bl) * 18 + 2 * cpl;
;       if (!upd && cpl >= 8) continue;
.LBB0_126:
	v_readlane_b32 s2, v253, 4
	s_add_i32 s101, s101, s2
	s_mov_b32 s46, s101
	s_cmp_lg_u32 s2, 64
	s_cbranch_scc1 .Lperm_done
	s_cmp_ge_i32 s101, 0x100
	s_cbranch_scc1 .LBB0_180
	s_cmp_lt_i32 s101, 0xc0
	s_cbranch_scc1 .Lperm_done
	s_cmp_lg_u32 s14, 0xc8
	s_cbranch_scc1 .Lperm_l0
	s_sub_i32 s2, s101, 0xc0
	s_mov_b32 s46, 0x7fff
	s_cmp_ge_u32 s2, 4
	s_cbranch_scc0 .Lperm_done
	s_cmp_lt_u32 s2, 8
	s_cbranch_scc0 .Lperm_hi
	s_add_i32 s46, s2, 0xc0
	s_branch .Lperm_done
.Lperm_hi:
	s_sub_i32 s2, s2, 32
	s_cmp_lt_u32 s2, 4
	s_cbranch_scc0 .Lperm_done
	s_add_i32 s46, s2, 0xc0
	s_branch .Lperm_done
.Lperm_l0:
	s_add_i32 s46, s101, 40
	s_and_b32 s46, s46, 63
	s_addk_i32 s46, 0xc0
